# attention K/V prefetch addresses: SGPR base advanced by SALU + loop-invariant VGPR lane offsets (no per-load 64-bit VALU adds)
# speedup vs baseline: 1.0022x; 1.0022x over previous
.LBB0_578:
	s_or_b64 exec, exec, s[68:69]
	s_mov_b32 s41, s53
	s_lshl_b64 s[68:69], s[40:41], 10
	s_add_u32 s37, s46, s68
	s_addc_u32 s48, s47, s69
	s_lshl_b32 s3, s22, 1
	s_add_u32 s37, s37, s3
	s_addc_u32 s48, s48, 0
	s_add_u32 s60, s37, 0xab00000
	s_addc_u32 s61, s48, 0
	v_and_b32_e32 v27, 15, v18
	v_lshlrev_b64 v[32:33], 10, v[22:23]
	s_lshl_b32 s52, s22, 16
	v_lshlrev_b32_e32 v176, 4, v27
	v_lshl_add_u64 v[32:33], s[60:61], 0, v[32:33]
	s_add_u32 s37, s42, s52
	v_lshl_add_u64 v[36:37], v[32:33], 0, v[176:177]
	s_mov_b32 s7, 0x8000
	s_addc_u32 s48, s43, 0
	s_lshl_b64 s[70:71], s[40:41], 1
	v_ashrrev_i32_e32 v34, 3, v18
	v_lshl_add_u64 v[30:31], s[60:61], 0, v[16:17]
	v_add_co_u32_e64 v32, s[40:41], s7, v36
	s_add_u32 s62, s37, s70
	v_lshl_add_u64 v[30:31], v[30:31], 0, v[176:177]
	v_addc_co_u32_e64 v33, s[40:41], 0, v37, s[40:41]
	v_ashrrev_i32_e32 v35, 31, v34
	s_addc_u32 s63, s48, s71
	v_and_b32_e32 v29, 7, v18
	flat_load_dwordx4 v[96:99], v[30:31]
	flat_load_dwordx4 v[100:103], v[32:33]
	v_lshlrev_b64 v[32:33], 16, v[34:35]
	v_lshl_add_u64 v[38:39], s[62:63], 0, v[32:33]
	v_lshlrev_b32_e32 v30, 4, v29
	v_mov_b32_e32 v31, v177
	v_lshl_add_u64 v[38:39], v[38:39], 0, v[30:31]
	s_mov_b32 s7, 0xcb00000
	s_mov_b64 s[14:15], 0xcb00000
	v_add_co_u32_e64 v42, s[40:41], s7, v38
	v_lshl_add_u64 v[40:41], v[38:39], 0, s[14:15]
	s_nop 0
	v_addc_co_u32_e64 v43, s[40:41], 0, v39, s[40:41]
	s_mov_b64 s[14:15], 0xcf00000
	s_mov_b32 s7, 0xcf00000
	v_lshl_add_u64 v[44:45], v[38:39], 0, s[14:15]
	v_add_co_u32_e64 v38, s[40:41], s7, v38
	v_readlane_b32 s7, v255, 23
	s_nop 0
	v_addc_co_u32_e64 v39, s[40:41], 0, v39, s[40:41]
	v_add_co_u32_e64 v46, s[40:41], s9, v36
	s_nop 1
	v_addc_co_u32_e64 v47, s[40:41], 0, v37, s[40:41]
	v_add_co_u32_e64 v36, s[40:41], s10, v36
	s_nop 1
	v_addc_co_u32_e64 v37, s[40:41], 0, v37, s[40:41]
	flat_load_dwordx4 v[104:107], v[46:47]
	flat_load_dwordx4 v[108:111], v[36:37]
	flat_load_dwordx4 v[120:123], v[42:43]
	flat_load_dwordx4 v[112:115], v[40:41] offset:128
	flat_load_dwordx4 v[124:127], v[38:39]
	flat_load_dwordx4 v[116:119], v[44:45] offset:128
	v_add_u32_e32 v36, s7, v20
	v_mul_lo_u32 v20, v22, s12
	v_add_u32_e32 v22, v36, v20
	s_waitcnt vmcnt(0) lgkmcnt(0)
	v_lshlrev_b32_e32 v84, 2, v18
	v_add_u32_e32 v84, 0x1ac00, v84
	ds_write_b32 v84, v88
	v_lshlrev_b32_e32 v85, 2, v85
	v_add_u32_e32 v85, 0x1ac00, v85
	ds_write_b32 v85, v89
	ds_write_b128 v22, v[4:7]
	v_mad_u64_u32 v[4:5], s[40:41], v24, s12, v[36:37]
	ds_write_b128 v4, v[0:3]
	v_mad_u64_u32 v[0:1], s[40:41], v26, s12, v[36:37]
	ds_write_b128 v0, v[12:15]
	v_mad_u64_u32 v[0:1], s[40:41], v28, s12, v[36:37]
	ds_write_b128 v0, v[8:11]
	v_lshl_add_u32 v0, v18, 2, 0
	v_add_u32_e32 v1, 0x11800, v0
	ds_write_b32 v1, v21
	s_and_saveexec_b64 s[40:41], vcc
	ds_write_b32 v1, v25 offset:2048
	s_or_b64 exec, exec, s[40:41]
	s_and_saveexec_b64 s[40:41], s[0:1]
	v_add_u32_e32 v0, 0x1a900, v0
	ds_write_b32 v0, v19
	s_or_b64 exec, exec, s[40:41]
	s_ashr_i32 s60, s58, 8
	s_lshl_b32 s0, s60, 7
	s_bfe_u32 s61, s58, 0x20006
	s_add_i32 s1, s0, 0
	v_and_b32_e32 v2, 31, v18
	s_lshl_b32 s37, s61, 5
	s_add_i32 s1, s1, 0x12100
	v_or_b32_e32 v1, s37, v2
	v_mov_b32_e32 v3, s1
	v_lshlrev_b32_e32 v0, 3, v18
	v_mad_u32_u24 v3, v1, s12, v3
	v_add_u32_e32 v1, 0, v20
	s_movk_i32 s1, 0x90
	v_and_b32_e32 v0, 8, v0
	v_add_u32_e32 v239, v1, v176
	v_mul_lo_u32 v1, v34, s1
	v_and_or_b32 v0, v30, s8, v0
	v_add_u32_e32 v1, 0, v1
	v_add_u32_e32 v240, v1, v0
	s_mul_i32 s1, s60, 0x410
	v_mad_u32_u24 v0, v2, s12, 0
	s_add_i32 s62, s1, 0
	s_or_b32 s72, s37, s73
	v_add_u32_e32 v4, s0, v0
	s_lshl_b32 s0, s77, 4
	s_lshr_b32 s59, s58, 6
	s_add_i32 s62, s62, 0x11800
	s_add_i32 s63, s72, 0x9f
	s_addk_i32 s72, 0x5f
	s_and_b32 s0, s0, 0x300
	v_bfe_u32 v236, v18, 5, 1
	v_lshlrev_b32_e32 v1, 7, v2
	s_add_u32 s0, s0, s68
	v_lshlrev_b32_e32 v237, 4, v236
	v_sub_u32_e32 v0, v0, v1
	s_addc_u32 s1, 0, s69
	v_add_u32_e32 v243, v0, v237
	v_lshl_add_u64 v[0:1], s[0:1], 0, v[16:17]
	v_lshl_add_u64 v[0:1], v[0:1], 0, v[176:177]
	v_lshl_add_u64 v[0:1], s[46:47], 0, v[0:1]
	s_mov_b64 s[0:1], 0xab38000
	v_lshl_add_u64 v[190:191], v[0:1], 0, s[0:1]
	v_lshl_add_u64 v[0:1], s[52:53], 0, v[32:33]
	v_mov_b32_e32 v31, v177
	s_add_u32 s0, s42, s70
	v_lshl_add_u64 v[0:1], v[0:1], 0, v[30:31]
	s_addc_u32 s1, s43, s71
	v_lshlrev_b32_e32 v235, 2, v236
	v_lshl_add_u64 v[0:1], s[0:1], 0, v[0:1]
	s_mov_b64 s[0:1], 0xcf00180
	v_lshl_add_u64 v[192:193], v[0:1], 0, s[0:1]
	s_nop 3
	v_readfirstlane_b32 s84, v190
	v_readfirstlane_b32 s85, v191
	s_nop 3
	v_subrev_u32_e32 v190, s84, v190
	v_add_u32_e32 v191, 0x8000, v190
	s_add_u32 s84, s84, 0xfffe8000
	s_addc_u32 s85, s85, -1
	v_readfirstlane_b32 s26, v192
	v_readfirstlane_b32 s27, v193
	s_nop 3
	v_subrev_u32_e32 v192, s26, v192
	v_add_u32_e32 v193, 0x400000, v192
	s_add_u32 s26, s26, 0xffbfff80
	s_addc_u32 s27, s27, -1
	v_sub_u32_e32 v0, v235, v2
	v_subrev_u32_e32 v0, s37, v0
	s_add_i32 s0, s37, s73
	v_mov_b32_e32 v248, 0
	v_lshlrev_b32_e32 v233, 3, v27
	v_and_b32_e32 v234, 63, v18
	v_add_u32_e32 v241, 0x8800, v240
	v_add_u32_e32 v242, 0xa800, v240
	v_mul_u32_u24_e32 v238, 0x110, v2
	v_add_u32_e32 v244, 0xd000, v243
	v_subrev_u32_e32 v245, s73, v0
	s_mov_b32 s22, 0
	s_sub_i32 s46, 0, s0
	v_add_u32_e32 v246, v4, v237
	v_add_u32_e32 v247, v3, v237
	s_mov_b32 s47, 0
	v_mov_b32_e32 v0, 0
	v_mov_b32_e32 v1, v248
	v_mov_b32_e32 v2, v248
	v_mov_b32_e32 v3, v248
	v_mov_b32_e32 v4, v248
	v_mov_b32_e32 v5, v248
	v_mov_b32_e32 v6, v248
	v_mov_b32_e32 v7, v248
	v_mov_b32_e32 v8, v248
	v_mov_b32_e32 v9, v248
	v_mov_b32_e32 v10, v248
	v_mov_b32_e32 v11, v248
	v_mov_b32_e32 v12, v248
	v_mov_b32_e32 v13, v248
	v_mov_b32_e32 v14, v248
	v_mov_b32_e32 v15, v248
	v_mov_b32_e32 v16, 0
	v_mov_b32_e32 v17, v248
	v_mov_b32_e32 v18, v248
	v_mov_b32_e32 v19, v248
	v_mov_b32_e32 v20, v248
	v_mov_b32_e32 v21, v248
	v_mov_b32_e32 v22, v248
	v_mov_b32_e32 v23, v248
	v_mov_b32_e32 v24, v248
	v_mov_b32_e32 v25, v248
	v_mov_b32_e32 v26, v248
	v_mov_b32_e32 v27, v248
	v_mov_b32_e32 v28, v248
	v_mov_b32_e32 v29, v248
	v_mov_b32_e32 v30, v248
	v_mov_b32_e32 v31, v248
	v_mov_b32_e32 v32, 0
	v_mov_b32_e32 v33, v248
	v_mov_b32_e32 v34, v248
	v_mov_b32_e32 v35, v248
	v_mov_b32_e32 v36, v248
	v_mov_b32_e32 v37, v248
	v_mov_b32_e32 v38, v248
	v_mov_b32_e32 v39, v248
	v_mov_b32_e32 v40, v248
	v_mov_b32_e32 v41, v248
	v_mov_b32_e32 v42, v248
	v_mov_b32_e32 v43, v248
	v_mov_b32_e32 v44, v248
	v_mov_b32_e32 v45, v248
	v_mov_b32_e32 v46, v248
	v_mov_b32_e32 v47, v248
	v_mov_b32_e32 v48, 0
	v_mov_b32_e32 v49, v248
	v_mov_b32_e32 v50, v248
	v_mov_b32_e32 v51, v248
	v_mov_b32_e32 v52, v248
	v_mov_b32_e32 v53, v248
	v_mov_b32_e32 v54, v248
	v_mov_b32_e32 v55, v248
	v_mov_b32_e32 v56, v248
	v_mov_b32_e32 v57, v248
	v_mov_b32_e32 v58, v248
	v_mov_b32_e32 v59, v248
	v_mov_b32_e32 v60, v248
	v_mov_b32_e32 v61, v248
	v_mov_b32_e32 v62, v248
	v_mov_b32_e32 v63, v248
	ds_write_b128 v239, v[96:99]
	ds_write_b128 v239, v[100:103] offset:8704
	ds_write2_b64 v241, v[120:121], v[122:123] offset1:2
	ds_write2_b64 v242, v[124:125], v[126:127] offset0:128 offset1:130
	s_waitcnt lgkmcnt(0)
	s_barrier
	ds_read_b128 v[222:225], v247
	ds_read_b128 v[218:221], v247 offset:32
	ds_read_b128 v[214:217], v247 offset:64
	ds_read_b128 v[210:213], v247 offset:96
	s_mov_b32 s100, -1
	s_branch .LBB0_584
.LBB0_583:
	s_waitcnt lgkmcnt(0)
	s_barrier
	s_add_i32 s47, s47, 2
	s_addk_i32 s22, 0x80
	s_and_b64 vcc, exec, s[0:1]
	s_cbranch_vccnz .LBB0_598

.La1t0_cb:
	v_add_u32_e32 v249, s22, v245
	ds_read_b128 v[128:131], v243 offset:44032
	ds_read_b128 v[132:135], v243 offset:44064
	ds_read_b128 v[136:139], v243 offset:48640
	ds_read_b128 v[140:143], v243 offset:48672
	s_cmp_eq_u64 s[40:41], 0
	s_waitcnt lgkmcnt(11)
	v_mfma_f32_32x32x16_bf16 v[64:79], v[172:175], v[222:225], v[194:209]
	s_cbranch_scc1 .La1t0_nl0
	global_load_dwordx4 v[96:99], v190, s[84:85]
.La1t0_nl0:
	s_waitcnt lgkmcnt(10)
	v_mfma_f32_32x32x16_bf16 v[64:79], v[168:171], v[218:221], v[64:79]
	s_cbranch_scc1 .La1t0_nl1
	global_load_dwordx4 v[100:103], v191, s[84:85]
.La1t0_nl1:
	s_waitcnt lgkmcnt(9)
	v_mfma_f32_32x32x16_bf16 v[64:79], v[164:167], v[214:217], v[64:79]
	s_cbranch_scc1 .La1t0_nl2
	global_load_dwordx4 v[120:123], v192, s[26:27]
.La1t0_nl2:
	s_waitcnt lgkmcnt(8)
	v_mfma_f32_32x32x16_bf16 v[64:79], v[160:163], v[210:213], v[64:79]
	s_cbranch_scc1 .La1t0_nl3
	global_load_dwordx4 v[124:127], v193, s[26:27]
.La1t0_nl3:
	s_add_u32 s84, s84, 0x10000
	s_addc_u32 s85, s85, 0
	s_add_u32 s26, s26, 0x80
	s_addc_u32 s27, s27, 0
	s_waitcnt lgkmcnt(7)
	v_mfma_f32_32x32x16_bf16 v[80:95], v[156:159], v[222:225], v[194:209]
	s_nop 11
	v_exp_f32_e32 v64, v64
	v_exp_f32_e32 v65, v65
	v_exp_f32_e32 v66, v66
	v_exp_f32_e32 v67, v67
	v_exp_f32_e32 v68, v68
	v_exp_f32_e32 v69, v69
	s_waitcnt lgkmcnt(6)
	v_mfma_f32_32x32x16_bf16 v[80:95], v[152:155], v[218:221], v[80:95]
	v_exp_f32_e32 v70, v70
	v_exp_f32_e32 v71, v71
	v_exp_f32_e32 v72, v72
	v_exp_f32_e32 v73, v73
	v_exp_f32_e32 v74, v74
	v_exp_f32_e32 v75, v75
	s_waitcnt lgkmcnt(5)
	v_mfma_f32_32x32x16_bf16 v[80:95], v[148:151], v[214:217], v[80:95]
	v_exp_f32_e32 v76, v76
	v_exp_f32_e32 v77, v77
	v_exp_f32_e32 v78, v78
	v_exp_f32_e32 v79, v79
	v_cvt_pk_bf16_f32 v160, v64, v65
	v_cvt_pk_bf16_f32 v161, v66, v67
	s_waitcnt lgkmcnt(4)
	v_mfma_f32_32x32x16_bf16 v[80:95], v[144:147], v[210:213], v[80:95]
	ds_read_b128 v[144:147], v243 offset:34816
	ds_read_b128 v[148:151], v243 offset:34848
	ds_read_b128 v[152:155], v243 offset:39424
	ds_read_b128 v[156:159], v243 offset:39456
	v_cvt_pk_bf16_f32 v162, v68, v69
	v_cvt_pk_bf16_f32 v163, v70, v71
	v_cvt_pk_bf16_f32 v164, v72, v73
	v_cvt_pk_bf16_f32 v165, v74, v75
	v_cvt_pk_bf16_f32 v166, v76, v77
	v_cvt_pk_bf16_f32 v167, v78, v79
	s_nop 4
	v_exp_f32_e32 v80, v80
	v_exp_f32_e32 v81, v81
	v_exp_f32_e32 v82, v82
	v_exp_f32_e32 v83, v83
	s_waitcnt lgkmcnt(7)
	v_mfma_f32_32x32x16_bf16 v[16:31], v[128:131], v[160:163], v[16:31]
	s_cmp_eq_u64 s[40:41], 0
	s_cbranch_scc1 .La1t0_lv_a
	s_waitcnt vmcnt(4)
	s_branch .La1t0_lv_b

.La1t0_near:
	v_add_u32_e32 v249, s22, v245
	s_mul_i32 s101, s60, 0x704
	s_add_i32 s101, s101, 0x1af80
	v_lshl_add_u32 v251, v249, 2, s101
	ds_read_b32 v64, v251 offset:0
	ds_read_b32 v65, v251 offset:4
	ds_read_b32 v66, v251 offset:8
	ds_read_b32 v67, v251 offset:12
	ds_read_b32 v68, v251 offset:32
	ds_read_b32 v69, v251 offset:36
	ds_read_b32 v70, v251 offset:40
	ds_read_b32 v71, v251 offset:44
	ds_read_b32 v72, v251 offset:64
	ds_read_b32 v73, v251 offset:68
	ds_read_b32 v74, v251 offset:72
	ds_read_b32 v75, v251 offset:76
	ds_read_b32 v76, v251 offset:96
	ds_read_b32 v77, v251 offset:100
	ds_read_b32 v78, v251 offset:104
	ds_read_b32 v79, v251 offset:108
	ds_read_b32 v80, v251 offset:128
	ds_read_b32 v81, v251 offset:132
	ds_read_b32 v82, v251 offset:136
	ds_read_b32 v83, v251 offset:140
	ds_read_b32 v84, v251 offset:160
	ds_read_b32 v85, v251 offset:164
	ds_read_b32 v86, v251 offset:168
	ds_read_b32 v87, v251 offset:172
	ds_read_b32 v88, v251 offset:192
	ds_read_b32 v89, v251 offset:196
	ds_read_b32 v90, v251 offset:200
	ds_read_b32 v91, v251 offset:204
	ds_read_b32 v92, v251 offset:224
	ds_read_b32 v93, v251 offset:228
	ds_read_b32 v94, v251 offset:232
	ds_read_b32 v95, v251 offset:236
	s_waitcnt lgkmcnt(0)
	ds_read_b128 v[128:131], v243 offset:44032
	ds_read_b128 v[132:135], v243 offset:44064
	ds_read_b128 v[136:139], v243 offset:48640
	ds_read_b128 v[140:143], v243 offset:48672
	s_cmp_eq_u64 s[40:41], 0
	v_mfma_f32_32x32x16_bf16 v[64:79], v[172:175], v[222:225], v[64:79]
	s_cbranch_scc1 .La1t0n_nl0
	global_load_dwordx4 v[96:99], v190, s[84:85]
.La1t0n_nl0:
	v_mfma_f32_32x32x16_bf16 v[64:79], v[168:171], v[218:221], v[64:79]
	s_cbranch_scc1 .La1t0n_nl1
	global_load_dwordx4 v[100:103], v191, s[84:85]
.La1t0n_nl1:
	v_mfma_f32_32x32x16_bf16 v[64:79], v[164:167], v[214:217], v[64:79]
	s_cbranch_scc1 .La1t0n_nl2
	global_load_dwordx4 v[120:123], v192, s[26:27]
.La1t0n_nl2:
	v_mfma_f32_32x32x16_bf16 v[64:79], v[160:163], v[210:213], v[64:79]
	s_cbranch_scc1 .La1t0n_nl3
	global_load_dwordx4 v[124:127], v193, s[26:27]
.La1t0n_nl3:
	s_add_u32 s84, s84, 0x10000
	s_addc_u32 s85, s85, 0
	s_add_u32 s26, s26, 0x80
	s_addc_u32 s27, s27, 0
	v_mfma_f32_32x32x16_bf16 v[80:95], v[156:159], v[222:225], v[80:95]
	s_nop 11
	v_exp_f32_e32 v64, v64
	v_exp_f32_e32 v65, v65
	v_exp_f32_e32 v66, v66
	v_exp_f32_e32 v67, v67
	v_exp_f32_e32 v68, v68
	v_exp_f32_e32 v69, v69
	v_mfma_f32_32x32x16_bf16 v[80:95], v[152:155], v[218:221], v[80:95]
	v_exp_f32_e32 v70, v70
	v_exp_f32_e32 v71, v71
	v_exp_f32_e32 v72, v72
	v_exp_f32_e32 v73, v73
	v_exp_f32_e32 v74, v74
	v_exp_f32_e32 v75, v75
	v_mfma_f32_32x32x16_bf16 v[80:95], v[148:151], v[214:217], v[80:95]
	v_exp_f32_e32 v76, v76
	v_exp_f32_e32 v77, v77
	v_exp_f32_e32 v78, v78
	v_exp_f32_e32 v79, v79
	v_cvt_pk_bf16_f32 v160, v64, v65
	v_cvt_pk_bf16_f32 v161, v66, v67
	v_mfma_f32_32x32x16_bf16 v[80:95], v[144:147], v[210:213], v[80:95]
	ds_read_b128 v[144:147], v243 offset:34816
	ds_read_b128 v[148:151], v243 offset:34848
	ds_read_b128 v[152:155], v243 offset:39424
	ds_read_b128 v[156:159], v243 offset:39456
	v_cvt_pk_bf16_f32 v162, v68, v69
	v_cvt_pk_bf16_f32 v163, v70, v71
	v_cvt_pk_bf16_f32 v164, v72, v73
	v_cvt_pk_bf16_f32 v165, v74, v75
	v_cvt_pk_bf16_f32 v166, v76, v77
	v_cvt_pk_bf16_f32 v167, v78, v79
	s_nop 4
	v_exp_f32_e32 v80, v80
	v_exp_f32_e32 v81, v81
	v_exp_f32_e32 v82, v82
	v_exp_f32_e32 v83, v83
	s_waitcnt lgkmcnt(7)
	v_mfma_f32_32x32x16_bf16 v[16:31], v[128:131], v[160:163], v[16:31]
	s_cmp_eq_u64 s[40:41], 0
	s_cbranch_scc1 .La1t0n_lv_a
	s_waitcnt vmcnt(4)
	s_branch .La1t0n_lv_b

.La1t1_cb:
	ds_read_b128 v[128:131], v243 offset:62464
	ds_read_b128 v[132:135], v243 offset:62496
	ds_read_b128 v[136:139], v244 offset:13824
	ds_read_b128 v[140:143], v244 offset:13856
	s_cmp_eq_u64 s[40:41], 0
	s_waitcnt lgkmcnt(11)
	v_mfma_f32_32x32x16_bf16 v[64:79], v[172:175], v[222:225], v[194:209]
	s_cbranch_scc1 .La1t1_nl0
	global_load_dwordx4 v[104:107], v190, s[84:85]
.La1t1_nl0:
	s_waitcnt lgkmcnt(10)
	v_mfma_f32_32x32x16_bf16 v[64:79], v[168:171], v[218:221], v[64:79]
	s_cbranch_scc1 .La1t1_nl1
	global_load_dwordx4 v[108:111], v191, s[84:85]
.La1t1_nl1:
	s_waitcnt lgkmcnt(9)
	v_mfma_f32_32x32x16_bf16 v[64:79], v[164:167], v[214:217], v[64:79]
	s_cbranch_scc1 .La1t1_nl2
	global_load_dwordx4 v[112:115], v192, s[26:27]
.La1t1_nl2:
	s_waitcnt lgkmcnt(8)
	v_mfma_f32_32x32x16_bf16 v[64:79], v[160:163], v[210:213], v[64:79]
	s_cbranch_scc1 .La1t1_nl3
	global_load_dwordx4 v[116:119], v193, s[26:27]
.La1t1_nl3:
	s_add_u32 s84, s84, 0x10000
	s_addc_u32 s85, s85, 0
	s_add_u32 s26, s26, 0x80
	s_addc_u32 s27, s27, 0
	s_waitcnt lgkmcnt(7)
	v_mfma_f32_32x32x16_bf16 v[80:95], v[156:159], v[222:225], v[194:209]
	s_nop 11
	v_exp_f32_e32 v64, v64
	v_exp_f32_e32 v65, v65
	v_exp_f32_e32 v66, v66
	v_exp_f32_e32 v67, v67
	v_exp_f32_e32 v68, v68
	v_exp_f32_e32 v69, v69
	s_waitcnt lgkmcnt(6)
	v_mfma_f32_32x32x16_bf16 v[80:95], v[152:155], v[218:221], v[80:95]
	v_exp_f32_e32 v70, v70
	v_exp_f32_e32 v71, v71
	v_exp_f32_e32 v72, v72
	v_exp_f32_e32 v73, v73
	v_exp_f32_e32 v74, v74
	v_exp_f32_e32 v75, v75
	s_waitcnt lgkmcnt(5)
	v_mfma_f32_32x32x16_bf16 v[80:95], v[148:151], v[214:217], v[80:95]
	v_exp_f32_e32 v76, v76
	v_exp_f32_e32 v77, v77
	v_exp_f32_e32 v78, v78
	v_exp_f32_e32 v79, v79
	v_cvt_pk_bf16_f32 v160, v64, v65
	v_cvt_pk_bf16_f32 v161, v66, v67
	s_waitcnt lgkmcnt(4)
	v_mfma_f32_32x32x16_bf16 v[80:95], v[144:147], v[210:213], v[80:95]
	ds_read_b128 v[144:147], v243 offset:53248
	ds_read_b128 v[148:151], v243 offset:53280
	ds_read_b128 v[152:155], v243 offset:57856
	ds_read_b128 v[156:159], v243 offset:57888
	v_cvt_pk_bf16_f32 v162, v68, v69
	v_cvt_pk_bf16_f32 v163, v70, v71
	v_cvt_pk_bf16_f32 v164, v72, v73
	v_cvt_pk_bf16_f32 v165, v74, v75
	v_cvt_pk_bf16_f32 v166, v76, v77
	v_cvt_pk_bf16_f32 v167, v78, v79
	s_nop 4
	v_exp_f32_e32 v80, v80
	v_exp_f32_e32 v81, v81
	v_exp_f32_e32 v82, v82
	v_exp_f32_e32 v83, v83
	s_waitcnt lgkmcnt(7)
	v_mfma_f32_32x32x16_bf16 v[16:31], v[128:131], v[160:163], v[16:31]
	s_cmp_eq_u64 s[40:41], 0
	s_cbranch_scc1 .La1t1_lv_s
	s_waitcnt vmcnt(4)
	ds_write_b128 v239, v[96:99]
	ds_write_b128 v239, v[100:103] offset:8704
	ds_write2_b64 v241, v[120:121], v[122:123] offset1:2
	ds_write2_b64 v242, v[124:125], v[126:127] offset0:128 offset1:130

.La1t1_near:
	s_mul_i32 s101, s60, 0x704
	s_add_i32 s101, s101, 0x1b080
	v_lshl_add_u32 v251, v249, 2, s101
	ds_read_b32 v64, v251 offset:0
	ds_read_b32 v65, v251 offset:4
	ds_read_b32 v66, v251 offset:8
	ds_read_b32 v67, v251 offset:12
	ds_read_b32 v68, v251 offset:32
	ds_read_b32 v69, v251 offset:36
	ds_read_b32 v70, v251 offset:40
	ds_read_b32 v71, v251 offset:44
	ds_read_b32 v72, v251 offset:64
	ds_read_b32 v73, v251 offset:68
	ds_read_b32 v74, v251 offset:72
	ds_read_b32 v75, v251 offset:76
	ds_read_b32 v76, v251 offset:96
	ds_read_b32 v77, v251 offset:100
	ds_read_b32 v78, v251 offset:104
	ds_read_b32 v79, v251 offset:108
	ds_read_b32 v80, v251 offset:128
	ds_read_b32 v81, v251 offset:132
	ds_read_b32 v82, v251 offset:136
	ds_read_b32 v83, v251 offset:140
	ds_read_b32 v84, v251 offset:160
	ds_read_b32 v85, v251 offset:164
	ds_read_b32 v86, v251 offset:168
	ds_read_b32 v87, v251 offset:172
	ds_read_b32 v88, v251 offset:192
	ds_read_b32 v89, v251 offset:196
	ds_read_b32 v90, v251 offset:200
	ds_read_b32 v91, v251 offset:204
	ds_read_b32 v92, v251 offset:224
	ds_read_b32 v93, v251 offset:228
	ds_read_b32 v94, v251 offset:232
	ds_read_b32 v95, v251 offset:236
	s_waitcnt lgkmcnt(0)
	ds_read_b128 v[128:131], v243 offset:62464
	ds_read_b128 v[132:135], v243 offset:62496
	ds_read_b128 v[136:139], v244 offset:13824
	ds_read_b128 v[140:143], v244 offset:13856
	s_cmp_eq_u64 s[40:41], 0
	v_mfma_f32_32x32x16_bf16 v[64:79], v[172:175], v[222:225], v[64:79]
	s_cbranch_scc1 .La1t1n_nl0
	global_load_dwordx4 v[104:107], v190, s[84:85]
.La1t1n_nl0:
	v_mfma_f32_32x32x16_bf16 v[64:79], v[168:171], v[218:221], v[64:79]
	s_cbranch_scc1 .La1t1n_nl1
	global_load_dwordx4 v[108:111], v191, s[84:85]
.La1t1n_nl1:
	v_mfma_f32_32x32x16_bf16 v[64:79], v[164:167], v[214:217], v[64:79]
	s_cbranch_scc1 .La1t1n_nl2
	global_load_dwordx4 v[112:115], v192, s[26:27]
.La1t1n_nl2:
	v_mfma_f32_32x32x16_bf16 v[64:79], v[160:163], v[210:213], v[64:79]
	s_cbranch_scc1 .La1t1n_nl3
	global_load_dwordx4 v[116:119], v193, s[26:27]
.La1t1n_nl3:
	s_add_u32 s84, s84, 0x10000
	s_addc_u32 s85, s85, 0
	s_add_u32 s26, s26, 0x80
	s_addc_u32 s27, s27, 0
	v_mfma_f32_32x32x16_bf16 v[80:95], v[156:159], v[222:225], v[80:95]
	s_nop 11
	v_exp_f32_e32 v64, v64
	v_exp_f32_e32 v65, v65
	v_exp_f32_e32 v66, v66
	v_exp_f32_e32 v67, v67
	v_exp_f32_e32 v68, v68
	v_exp_f32_e32 v69, v69
	v_mfma_f32_32x32x16_bf16 v[80:95], v[152:155], v[218:221], v[80:95]
	v_exp_f32_e32 v70, v70
	v_exp_f32_e32 v71, v71
	v_exp_f32_e32 v72, v72
	v_exp_f32_e32 v73, v73
	v_exp_f32_e32 v74, v74
	v_exp_f32_e32 v75, v75
	v_mfma_f32_32x32x16_bf16 v[80:95], v[148:151], v[214:217], v[80:95]
	v_exp_f32_e32 v76, v76
	v_exp_f32_e32 v77, v77
	v_exp_f32_e32 v78, v78
	v_exp_f32_e32 v79, v79
	v_cvt_pk_bf16_f32 v160, v64, v65
	v_cvt_pk_bf16_f32 v161, v66, v67
	v_mfma_f32_32x32x16_bf16 v[80:95], v[144:147], v[210:213], v[80:95]
	ds_read_b128 v[144:147], v243 offset:53248
	ds_read_b128 v[148:151], v243 offset:53280
	ds_read_b128 v[152:155], v243 offset:57856
	ds_read_b128 v[156:159], v243 offset:57888
	v_cvt_pk_bf16_f32 v162, v68, v69
	v_cvt_pk_bf16_f32 v163, v70, v71
	v_cvt_pk_bf16_f32 v164, v72, v73
	v_cvt_pk_bf16_f32 v165, v74, v75
	v_cvt_pk_bf16_f32 v166, v76, v77
	v_cvt_pk_bf16_f32 v167, v78, v79
	s_nop 4
	v_exp_f32_e32 v80, v80
	v_exp_f32_e32 v81, v81
	v_exp_f32_e32 v82, v82
	v_exp_f32_e32 v83, v83
	s_waitcnt lgkmcnt(7)
	v_mfma_f32_32x32x16_bf16 v[16:31], v[128:131], v[160:163], v[16:31]
	s_cmp_eq_u64 s[40:41], 0
	s_cbranch_scc1 .La1t1n_lv_s
	s_waitcnt vmcnt(4)
	ds_write_b128 v239, v[96:99]
	ds_write_b128 v239, v[100:103] offset:8704
	ds_write2_b64 v241, v[120:121], v[122:123] offset1:2
	ds_write2_b64 v242, v[124:125], v[126:127] offset0:128 offset1:130

.LBB0_598:
	s_mov_b64 s[84:85], 0x20000
	s_mov_b64 s[26:27], 0x100
	v_lshlrev_b32_e32 v64, 2, v234
	v_xor_b32_e32 v67, 0x80, v64
	ds_bpermute_b32 v65, v67, v248
	s_lshl_b32 s0, s61, 14
	s_add_i32 s0, s0, 0
	s_cmp_eq_u32 s60, 1
	v_add_u32_e32 v64, s0, v64
	s_waitcnt lgkmcnt(0)
	v_add_f32_e32 v65, v248, v65
	s_cbranch_scc0 .LBB0_600
	v_div_scale_f32 v66, s[0:1], v65, v65, s74
	v_rcp_f32_e32 v68, v66
	v_div_scale_f32 v69, vcc, s74, v65, s74
	v_fma_f32 v70, -v66, v68, 1.0
	v_fmac_f32_e32 v68, v70, v68
	v_mul_f32_e32 v70, v69, v68
	v_fma_f32 v71, -v66, v70, v69
	v_fmac_f32_e32 v70, v71, v68
	v_fma_f32 v66, -v66, v70, v69
	v_div_fmas_f32 v66, v66, v68, v70
	v_div_fixup_f32 v66, v66, v65, s74
	v_mul_f32_e32 v68, v48, v66
	v_mul_f32_e32 v69, v49, v66
	ds_write2st64_b32 v64, v68, v69 offset1:1
	v_mul_f32_e32 v68, v50, v66
	v_mul_f32_e32 v69, v51, v66
	ds_write2st64_b32 v64, v68, v69 offset0:2 offset1:3
	v_mul_f32_e32 v68, v52, v66
	v_mul_f32_e32 v69, v53, v66
	ds_write2st64_b32 v64, v68, v69 offset0:4 offset1:5
	v_mul_f32_e32 v68, v54, v66
	v_mul_f32_e32 v69, v55, v66
	ds_write2st64_b32 v64, v68, v69 offset0:6 offset1:7
	v_mul_f32_e32 v68, v56, v66
	v_mul_f32_e32 v69, v57, v66
	ds_write2st64_b32 v64, v68, v69 offset0:8 offset1:9
	v_mul_f32_e32 v68, v58, v66
	v_mul_f32_e32 v69, v59, v66
	ds_write2st64_b32 v64, v68, v69 offset0:10 offset1:11
	v_mul_f32_e32 v68, v60, v66
	v_mul_f32_e32 v69, v61, v66
	ds_write2st64_b32 v64, v68, v69 offset0:12 offset1:13
	v_mul_f32_e32 v68, v62, v66
	v_mul_f32_e32 v69, v63, v66
	ds_write2st64_b32 v64, v68, v69 offset0:14 offset1:15
	v_mul_f32_e32 v68, v32, v66
	v_mul_f32_e32 v69, v33, v66
	ds_write2st64_b32 v64, v68, v69 offset0:16 offset1:17
	v_mul_f32_e32 v68, v34, v66
	v_mul_f32_e32 v69, v35, v66
	ds_write2st64_b32 v64, v68, v69 offset0:18 offset1:19
	v_mul_f32_e32 v68, v36, v66
	v_mul_f32_e32 v69, v37, v66
	ds_write2st64_b32 v64, v68, v69 offset0:20 offset1:21
	v_mul_f32_e32 v68, v38, v66
	v_mul_f32_e32 v69, v39, v66
	ds_write2st64_b32 v64, v68, v69 offset0:22 offset1:23
	v_mul_f32_e32 v68, v40, v66
	v_mul_f32_e32 v69, v41, v66
	ds_write2st64_b32 v64, v68, v69 offset0:24 offset1:25
	v_mul_f32_e32 v68, v42, v66
	v_mul_f32_e32 v69, v43, v66
	ds_write2st64_b32 v64, v68, v69 offset0:26 offset1:27
	v_mul_f32_e32 v68, v44, v66
	v_mul_f32_e32 v69, v45, v66
	ds_write2st64_b32 v64, v68, v69 offset0:28 offset1:29
	v_mul_f32_e32 v68, v46, v66
	v_mul_f32_e32 v69, v47, v66
	ds_write2st64_b32 v64, v68, v69 offset0:30 offset1:31
	v_mul_f32_e32 v68, v16, v66
	v_mul_f32_e32 v69, v17, v66
	ds_write2st64_b32 v64, v68, v69 offset0:32 offset1:33
	v_mul_f32_e32 v68, v18, v66
	v_mul_f32_e32 v69, v19, v66
	ds_write2st64_b32 v64, v68, v69 offset0:34 offset1:35
	v_mul_f32_e32 v68, v20, v66
	v_mul_f32_e32 v69, v21, v66
	ds_write2st64_b32 v64, v68, v69 offset0:36 offset1:37
	v_mul_f32_e32 v68, v22, v66
	v_mul_f32_e32 v69, v23, v66
	ds_write2st64_b32 v64, v68, v69 offset0:38 offset1:39
	v_mul_f32_e32 v68, v24, v66
	v_mul_f32_e32 v69, v25, v66
	ds_write2st64_b32 v64, v68, v69 offset0:40 offset1:41
	v_mul_f32_e32 v68, v26, v66
	v_mul_f32_e32 v69, v27, v66
	ds_write2st64_b32 v64, v68, v69 offset0:42 offset1:43
	v_mul_f32_e32 v68, v28, v66
	v_mul_f32_e32 v69, v29, v66
	ds_write2st64_b32 v64, v68, v69 offset0:44 offset1:45
	v_mul_f32_e32 v68, v30, v66
	v_mul_f32_e32 v69, v31, v66
	ds_write2st64_b32 v64, v68, v69 offset0:46 offset1:47
	v_mul_f32_e32 v68, v0, v66
	v_mul_f32_e32 v69, v1, v66
	ds_write2st64_b32 v64, v68, v69 offset0:48 offset1:49
	v_mul_f32_e32 v68, v2, v66
	v_mul_f32_e32 v69, v3, v66
	ds_write2st64_b32 v64, v68, v69 offset0:50 offset1:51
	v_mul_f32_e32 v68, v4, v66
	v_mul_f32_e32 v69, v5, v66
	ds_write2st64_b32 v64, v68, v69 offset0:52 offset1:53
	v_mul_f32_e32 v68, v6, v66
	v_mul_f32_e32 v69, v7, v66
	ds_write2st64_b32 v64, v68, v69 offset0:54 offset1:55
	v_mul_f32_e32 v68, v8, v66
	v_mul_f32_e32 v69, v9, v66
	ds_write2st64_b32 v64, v68, v69 offset0:56 offset1:57
	v_mul_f32_e32 v68, v10, v66
	v_mul_f32_e32 v69, v11, v66
	ds_write2st64_b32 v64, v68, v69 offset0:58 offset1:59
	v_mul_f32_e32 v68, v12, v66
	v_mul_f32_e32 v69, v13, v66
	ds_write2st64_b32 v64, v68, v69 offset0:60 offset1:61
	v_mul_f32_e32 v68, v14, v66
	v_mul_f32_e32 v66, v15, v66
	ds_write2st64_b32 v64, v68, v66 offset0:62 offset1:63

.LBB0_617:
	s_or_b64 exec, exec, s[70:71]
	s_ashr_i32 s41, s40, 31
	s_lshl_b64 s[70:71], s[40:41], 10
	s_add_u32 s37, s42, s70
	s_addc_u32 s48, s43, s71
	s_lshl_b32 s3, s22, 1
	s_add_u32 s37, s37, s3
	s_addc_u32 s48, s48, 0
	s_add_u32 s60, s37, 0xab00000
	s_addc_u32 s61, s48, 0
	v_and_b32_e32 v27, 15, v18
	v_lshlrev_b64 v[32:33], 10, v[22:23]
	s_lshl_b32 s52, s22, 16
	v_lshlrev_b32_e32 v176, 4, v27
	v_lshl_add_u64 v[32:33], s[60:61], 0, v[32:33]
	s_add_u32 s37, s46, s52
	v_lshl_add_u64 v[36:37], v[32:33], 0, v[176:177]
	s_mov_b32 s7, 0x8000
	s_addc_u32 s48, s47, 0
	s_lshl_b64 s[72:73], s[40:41], 1
	v_ashrrev_i32_e32 v34, 3, v18
	v_lshl_add_u64 v[30:31], s[60:61], 0, v[16:17]
	v_add_co_u32_e64 v32, s[40:41], s7, v36
	s_add_u32 s62, s37, s72
	v_lshl_add_u64 v[30:31], v[30:31], 0, v[176:177]
	v_addc_co_u32_e64 v33, s[40:41], 0, v37, s[40:41]
	v_ashrrev_i32_e32 v35, 31, v34
	s_addc_u32 s63, s48, s73
	v_and_b32_e32 v29, 7, v18
	global_load_dwordx4 v[96:99], v[30:31], off
	global_load_dwordx4 v[100:103], v[32:33], off
	v_lshlrev_b64 v[32:33], 16, v[34:35]
	v_lshl_add_u64 v[38:39], s[62:63], 0, v[32:33]
	v_lshlrev_b32_e32 v30, 4, v29
	v_mov_b32_e32 v31, v177
	v_lshl_add_u64 v[38:39], v[38:39], 0, v[30:31]
	s_mov_b32 s7, 0xcb00000
	s_mov_b64 s[14:15], 0xcb00000
	v_add_co_u32_e64 v42, s[40:41], s7, v38
	v_lshl_add_u64 v[40:41], v[38:39], 0, s[14:15]
	s_nop 0
	v_addc_co_u32_e64 v43, s[40:41], 0, v39, s[40:41]
	s_mov_b64 s[14:15], 0xcf00000
	s_mov_b32 s7, 0xcf00000
	v_lshl_add_u64 v[44:45], v[38:39], 0, s[14:15]
	v_add_co_u32_e64 v38, s[40:41], s7, v38
	v_readlane_b32 s7, v255, 23
	s_nop 0
	v_addc_co_u32_e64 v39, s[40:41], 0, v39, s[40:41]
	v_add_co_u32_e64 v46, s[40:41], s9, v36
	s_nop 1
	v_addc_co_u32_e64 v47, s[40:41], 0, v37, s[40:41]
	v_add_co_u32_e64 v36, s[40:41], s10, v36
	s_nop 1
	v_addc_co_u32_e64 v37, s[40:41], 0, v37, s[40:41]
	global_load_dwordx4 v[104:107], v[46:47], off
	global_load_dwordx4 v[108:111], v[36:37], off
	global_load_dwordx4 v[120:123], v[42:43], off
	global_load_dwordx4 v[112:115], v[40:41], off offset:128
	global_load_dwordx4 v[124:127], v[38:39], off
	global_load_dwordx4 v[116:119], v[44:45], off offset:128
	v_add_u32_e32 v36, s7, v20
	v_mul_lo_u32 v20, v22, s12
	v_add_u32_e32 v22, v36, v20
	s_waitcnt vmcnt(0) lgkmcnt(0)
	v_lshlrev_b32_e32 v84, 2, v18
	v_add_u32_e32 v84, 0x1ac00, v84
	ds_write_b32 v84, v88
	v_lshlrev_b32_e32 v85, 2, v85
	v_add_u32_e32 v85, 0x1ac00, v85
	ds_write_b32 v85, v89
	ds_write_b128 v22, v[4:7]
	v_mad_u64_u32 v[4:5], s[40:41], v24, s12, v[36:37]
	ds_write_b128 v4, v[0:3]
	v_mad_u64_u32 v[0:1], s[40:41], v26, s12, v[36:37]
	ds_write_b128 v0, v[12:15]
	v_mad_u64_u32 v[0:1], s[40:41], v28, s12, v[36:37]
	ds_write_b128 v0, v[8:11]
	v_lshl_add_u32 v0, v18, 2, 0
	v_add_u32_e32 v1, 0x11800, v0
	ds_write_b32 v1, v21
	s_and_saveexec_b64 s[40:41], vcc
	ds_write_b32 v1, v25 offset:2048
	s_or_b64 exec, exec, s[40:41]
	s_and_saveexec_b64 s[40:41], s[0:1]
	v_add_u32_e32 v0, 0x1a900, v0
	ds_write_b32 v0, v19
	s_or_b64 exec, exec, s[40:41]
	s_ashr_i32 s60, s58, 8
	s_lshl_b32 s40, s60, 7
	s_bfe_u32 s61, s58, 0x20006
	s_add_i32 s0, s40, 0
	s_lshr_b32 s59, s58, 6
	v_and_b32_e32 v2, 31, v18
	s_lshl_b32 s37, s61, 5
	s_add_i32 s0, s0, 0x12100
	v_or_b32_e32 v1, s37, v2
	v_mov_b32_e32 v3, s0
	s_and_b64 s[0:1], s[68:69], exec
	v_lshlrev_b32_e32 v0, 3, v18
	v_mad_u32_u24 v3, v1, s12, v3
	v_add_u32_e32 v1, 0, v20
	s_movk_i32 s0, 0x90
	v_and_b32_e32 v0, 8, v0
	v_add_u32_e32 v239, v1, v176
	v_mul_lo_u32 v1, v34, s0
	v_and_or_b32 v0, v30, s8, v0
	v_add_u32_e32 v1, 0, v1
	s_mul_i32 s0, s60, 0x410
	v_bfe_u32 v236, v18, 5, 1
	s_cselect_b32 s62, 32, 64
	v_add_u32_e32 v240, v1, v0
	s_add_i32 s63, s0, 0
	s_or_b32 s69, s37, s78
	v_mad_u32_u24 v0, v2, s12, 0
	v_lshlrev_b32_e32 v1, 7, v2
	v_lshlrev_b32_e32 v237, 4, v236
	s_add_i32 s63, s63, 0x11800
	v_add_u32_e32 v4, s40, v0
	v_sub_u32_e32 v0, v0, v1
	s_add_i32 s68, s69, 0x9f
	s_addk_i32 s69, 0x5f
	v_add_u32_e32 v243, v0, v237
	v_lshl_add_u64 v[0:1], s[52:53], 0, v[32:33]
	v_mov_b32_e32 v31, v177
	s_add_u32 s0, s46, s72
	v_lshl_add_u64 v[0:1], v[0:1], 0, v[30:31]
	s_addc_u32 s1, s47, s73
	v_lshl_add_u64 v[0:1], s[0:1], 0, v[0:1]
	s_mov_b64 s[0:1], 0xcf00180
	v_lshl_add_u64 v[190:191], v[0:1], 0, s[0:1]
	s_lshl_b32 s0, s77, 3
	s_and_b32 s0, s0, 0x300
	s_add_u32 s0, s0, s70
	s_addc_u32 s1, 0, s71
	v_lshl_add_u64 v[0:1], s[0:1], 0, v[16:17]
	v_lshl_add_u64 v[0:1], v[0:1], 0, v[176:177]
	v_lshlrev_b32_e32 v235, 2, v236
	v_lshl_add_u64 v[0:1], s[42:43], 0, v[0:1]
	s_mov_b64 s[0:1], 0xab38000
	v_lshl_add_u64 v[192:193], v[0:1], 0, s[0:1]
	s_nop 3
	v_readfirstlane_b32 s84, v192
	v_readfirstlane_b32 s85, v193
	s_nop 3
	v_subrev_u32_e32 v192, s84, v192
	v_add_u32_e32 v193, 0x8000, v192
	s_add_u32 s84, s84, 0xfffe8000
	s_addc_u32 s85, s85, -1
	v_readfirstlane_b32 s26, v190
	v_readfirstlane_b32 s27, v191
	s_nop 3
	v_subrev_u32_e32 v190, s26, v190
	v_add_u32_e32 v191, 0x400000, v190
	s_add_u32 s26, s26, 0xffbfff80
	s_addc_u32 s27, s27, -1
	v_sub_u32_e32 v0, v235, v2
	v_subrev_u32_e32 v0, s37, v0
	s_add_i32 s0, s37, s78
	v_mov_b32_e32 v248, 0
	v_lshlrev_b32_e32 v233, 3, v27
	v_and_b32_e32 v234, 63, v18
	v_add_u32_e32 v241, 0x8800, v240
	v_add_u32_e32 v242, 0xa800, v240
	v_mul_u32_u24_e32 v238, 0x110, v2
	v_add_u32_e32 v244, 0xd000, v243
	s_mov_b32 s22, 3
	v_subrev_u32_e32 v245, s78, v0
	s_mov_b32 s42, 0
	s_sub_i32 s43, 0, s0
	v_add_u32_e32 v246, v4, v237
	v_add_u32_e32 v247, v3, v237
	v_mov_b32_e32 v0, 0
	v_mov_b32_e32 v1, v248
	v_mov_b32_e32 v2, v248
	v_mov_b32_e32 v3, v248
	v_mov_b32_e32 v4, v248
	v_mov_b32_e32 v5, v248
	v_mov_b32_e32 v6, v248
	v_mov_b32_e32 v7, v248
	v_mov_b32_e32 v8, v248
	v_mov_b32_e32 v9, v248
	v_mov_b32_e32 v10, v248
	v_mov_b32_e32 v11, v248
	v_mov_b32_e32 v12, v248
	v_mov_b32_e32 v13, v248
	v_mov_b32_e32 v14, v248
	v_mov_b32_e32 v15, v248
	v_mov_b32_e32 v16, 0
	v_mov_b32_e32 v17, v248
	v_mov_b32_e32 v18, v248
	v_mov_b32_e32 v19, v248
	v_mov_b32_e32 v20, v248
	v_mov_b32_e32 v21, v248
	v_mov_b32_e32 v22, v248
	v_mov_b32_e32 v23, v248
	v_mov_b32_e32 v24, v248
	v_mov_b32_e32 v25, v248
	v_mov_b32_e32 v26, v248
	v_mov_b32_e32 v27, v248
	v_mov_b32_e32 v28, v248
	v_mov_b32_e32 v29, v248
	v_mov_b32_e32 v30, v248
	v_mov_b32_e32 v31, v248
	v_mov_b32_e32 v32, 0
	v_mov_b32_e32 v33, v248
	v_mov_b32_e32 v34, v248
	v_mov_b32_e32 v35, v248
	v_mov_b32_e32 v36, v248
	v_mov_b32_e32 v37, v248
	v_mov_b32_e32 v38, v248
	v_mov_b32_e32 v39, v248
	v_mov_b32_e32 v40, v248
	v_mov_b32_e32 v41, v248
	v_mov_b32_e32 v42, v248
	v_mov_b32_e32 v43, v248
	v_mov_b32_e32 v44, v248
	v_mov_b32_e32 v45, v248
	v_mov_b32_e32 v46, v248
	v_mov_b32_e32 v47, v248
	v_mov_b32_e32 v48, 0
	v_mov_b32_e32 v49, v248
	v_mov_b32_e32 v50, v248
	v_mov_b32_e32 v51, v248
	v_mov_b32_e32 v52, v248
	v_mov_b32_e32 v53, v248
	v_mov_b32_e32 v54, v248
	v_mov_b32_e32 v55, v248
	v_mov_b32_e32 v56, v248
	v_mov_b32_e32 v57, v248
	v_mov_b32_e32 v58, v248
	v_mov_b32_e32 v59, v248
	v_mov_b32_e32 v60, v248
	v_mov_b32_e32 v61, v248
	v_mov_b32_e32 v62, v248
	v_mov_b32_e32 v63, v248
	s_waitcnt vmcnt(0)
	ds_write_b128 v239, v[96:99]
	ds_write_b128 v239, v[100:103] offset:8704
	ds_write2_b64 v241, v[120:121], v[122:123] offset1:2
	ds_write2_b64 v242, v[124:125], v[126:127] offset0:128 offset1:130
	s_waitcnt lgkmcnt(0)
	s_barrier
	ds_read_b128 v[222:225], v247
	ds_read_b128 v[218:221], v247 offset:32
	ds_read_b128 v[214:217], v247 offset:64
	ds_read_b128 v[210:213], v247 offset:96
	s_mov_b32 s100, -1
	s_branch .LBB0_623
.LBB0_622:
	s_waitcnt lgkmcnt(0)
	s_barrier
	s_add_i32 s22, s22, 2
	s_addk_i32 s42, 0x80
	s_cmp_ge_u32 s46, s62
	s_cbranch_scc1 .LBB0_637

.La2t0_cb:
	v_add_u32_e32 v249, s42, v245
	ds_read_b128 v[128:131], v243 offset:44032
	ds_read_b128 v[132:135], v243 offset:44064
	ds_read_b128 v[136:139], v243 offset:48640
	ds_read_b128 v[140:143], v243 offset:48672
	s_cmp_eq_u64 s[0:1], 0
	s_waitcnt lgkmcnt(11)
	v_mfma_f32_32x32x16_bf16 v[64:79], v[172:175], v[222:225], v[194:209]
	s_cbranch_scc1 .La2t0_nl0
	global_load_dwordx4 v[96:99], v192, s[84:85]
.La2t0_nl0:
	s_waitcnt lgkmcnt(10)
	v_mfma_f32_32x32x16_bf16 v[64:79], v[168:171], v[218:221], v[64:79]
	s_cbranch_scc1 .La2t0_nl1
	global_load_dwordx4 v[100:103], v193, s[84:85]
.La2t0_nl1:
	s_waitcnt lgkmcnt(9)
	v_mfma_f32_32x32x16_bf16 v[64:79], v[164:167], v[214:217], v[64:79]
	s_cbranch_scc1 .La2t0_nl2
	global_load_dwordx4 v[120:123], v190, s[26:27]
.La2t0_nl2:
	s_waitcnt lgkmcnt(8)
	v_mfma_f32_32x32x16_bf16 v[64:79], v[160:163], v[210:213], v[64:79]
	s_cbranch_scc1 .La2t0_nl3
	global_load_dwordx4 v[124:127], v191, s[26:27]
.La2t0_nl3:
	s_add_u32 s84, s84, 0x10000
	s_addc_u32 s85, s85, 0
	s_add_u32 s26, s26, 0x80
	s_addc_u32 s27, s27, 0
	s_waitcnt lgkmcnt(7)
	v_mfma_f32_32x32x16_bf16 v[80:95], v[156:159], v[222:225], v[194:209]
	s_nop 11
	v_exp_f32_e32 v64, v64
	v_exp_f32_e32 v65, v65
	v_exp_f32_e32 v66, v66
	v_exp_f32_e32 v67, v67
	v_exp_f32_e32 v68, v68
	v_exp_f32_e32 v69, v69
	s_waitcnt lgkmcnt(6)
	v_mfma_f32_32x32x16_bf16 v[80:95], v[152:155], v[218:221], v[80:95]
	v_exp_f32_e32 v70, v70
	v_exp_f32_e32 v71, v71
	v_exp_f32_e32 v72, v72
	v_exp_f32_e32 v73, v73
	v_exp_f32_e32 v74, v74
	v_exp_f32_e32 v75, v75
	s_waitcnt lgkmcnt(5)
	v_mfma_f32_32x32x16_bf16 v[80:95], v[148:151], v[214:217], v[80:95]
	v_exp_f32_e32 v76, v76
	v_exp_f32_e32 v77, v77
	v_exp_f32_e32 v78, v78
	v_exp_f32_e32 v79, v79
	v_cvt_pk_bf16_f32 v160, v64, v65
	v_cvt_pk_bf16_f32 v161, v66, v67
	s_waitcnt lgkmcnt(4)
	v_mfma_f32_32x32x16_bf16 v[80:95], v[144:147], v[210:213], v[80:95]
	ds_read_b128 v[144:147], v243 offset:34816
	ds_read_b128 v[148:151], v243 offset:34848
	ds_read_b128 v[152:155], v243 offset:39424
	ds_read_b128 v[156:159], v243 offset:39456
	v_cvt_pk_bf16_f32 v162, v68, v69
	v_cvt_pk_bf16_f32 v163, v70, v71
	v_cvt_pk_bf16_f32 v164, v72, v73
	v_cvt_pk_bf16_f32 v165, v74, v75
	v_cvt_pk_bf16_f32 v166, v76, v77
	v_cvt_pk_bf16_f32 v167, v78, v79
	s_nop 4
	v_exp_f32_e32 v80, v80
	v_exp_f32_e32 v81, v81
	v_exp_f32_e32 v82, v82
	v_exp_f32_e32 v83, v83
	s_waitcnt lgkmcnt(7)
	v_mfma_f32_32x32x16_bf16 v[16:31], v[128:131], v[160:163], v[16:31]
	s_cmp_eq_u64 s[0:1], 0
	s_cbranch_scc1 .La2t0_lv_a
	s_waitcnt vmcnt(4)
	s_branch .La2t0_lv_b

.La2t0_near:
	v_add_u32_e32 v249, s42, v245
	s_mul_i32 s101, s60, 0x704
	s_add_i32 s101, s101, 0x1af80
	v_lshl_add_u32 v251, v249, 2, s101
	ds_read_b32 v64, v251 offset:0
	ds_read_b32 v65, v251 offset:4
	ds_read_b32 v66, v251 offset:8
	ds_read_b32 v67, v251 offset:12
	ds_read_b32 v68, v251 offset:32
	ds_read_b32 v69, v251 offset:36
	ds_read_b32 v70, v251 offset:40
	ds_read_b32 v71, v251 offset:44
	ds_read_b32 v72, v251 offset:64
	ds_read_b32 v73, v251 offset:68
	ds_read_b32 v74, v251 offset:72
	ds_read_b32 v75, v251 offset:76
	ds_read_b32 v76, v251 offset:96
	ds_read_b32 v77, v251 offset:100
	ds_read_b32 v78, v251 offset:104
	ds_read_b32 v79, v251 offset:108
	ds_read_b32 v80, v251 offset:128
	ds_read_b32 v81, v251 offset:132
	ds_read_b32 v82, v251 offset:136
	ds_read_b32 v83, v251 offset:140
	ds_read_b32 v84, v251 offset:160
	ds_read_b32 v85, v251 offset:164
	ds_read_b32 v86, v251 offset:168
	ds_read_b32 v87, v251 offset:172
	ds_read_b32 v88, v251 offset:192
	ds_read_b32 v89, v251 offset:196
	ds_read_b32 v90, v251 offset:200
	ds_read_b32 v91, v251 offset:204
	ds_read_b32 v92, v251 offset:224
	ds_read_b32 v93, v251 offset:228
	ds_read_b32 v94, v251 offset:232
	ds_read_b32 v95, v251 offset:236
	s_waitcnt lgkmcnt(0)
	ds_read_b128 v[128:131], v243 offset:44032
	ds_read_b128 v[132:135], v243 offset:44064
	ds_read_b128 v[136:139], v243 offset:48640
	ds_read_b128 v[140:143], v243 offset:48672
	s_cmp_eq_u64 s[0:1], 0
	v_mfma_f32_32x32x16_bf16 v[64:79], v[172:175], v[222:225], v[64:79]
	s_cbranch_scc1 .La2t0n_nl0
	global_load_dwordx4 v[96:99], v192, s[84:85]
.La2t0n_nl0:
	v_mfma_f32_32x32x16_bf16 v[64:79], v[168:171], v[218:221], v[64:79]
	s_cbranch_scc1 .La2t0n_nl1
	global_load_dwordx4 v[100:103], v193, s[84:85]
.La2t0n_nl1:
	v_mfma_f32_32x32x16_bf16 v[64:79], v[164:167], v[214:217], v[64:79]
	s_cbranch_scc1 .La2t0n_nl2
	global_load_dwordx4 v[120:123], v190, s[26:27]
.La2t0n_nl2:
	v_mfma_f32_32x32x16_bf16 v[64:79], v[160:163], v[210:213], v[64:79]
	s_cbranch_scc1 .La2t0n_nl3
	global_load_dwordx4 v[124:127], v191, s[26:27]
.La2t0n_nl3:
	s_add_u32 s84, s84, 0x10000
	s_addc_u32 s85, s85, 0
	s_add_u32 s26, s26, 0x80
	s_addc_u32 s27, s27, 0
	v_mfma_f32_32x32x16_bf16 v[80:95], v[156:159], v[222:225], v[80:95]
	s_nop 11
	v_exp_f32_e32 v64, v64
	v_exp_f32_e32 v65, v65
	v_exp_f32_e32 v66, v66
	v_exp_f32_e32 v67, v67
	v_exp_f32_e32 v68, v68
	v_exp_f32_e32 v69, v69
	v_mfma_f32_32x32x16_bf16 v[80:95], v[152:155], v[218:221], v[80:95]
	v_exp_f32_e32 v70, v70
	v_exp_f32_e32 v71, v71
	v_exp_f32_e32 v72, v72
	v_exp_f32_e32 v73, v73
	v_exp_f32_e32 v74, v74
	v_exp_f32_e32 v75, v75
	v_mfma_f32_32x32x16_bf16 v[80:95], v[148:151], v[214:217], v[80:95]
	v_exp_f32_e32 v76, v76
	v_exp_f32_e32 v77, v77
	v_exp_f32_e32 v78, v78
	v_exp_f32_e32 v79, v79
	v_cvt_pk_bf16_f32 v160, v64, v65
	v_cvt_pk_bf16_f32 v161, v66, v67
	v_mfma_f32_32x32x16_bf16 v[80:95], v[144:147], v[210:213], v[80:95]
	ds_read_b128 v[144:147], v243 offset:34816
	ds_read_b128 v[148:151], v243 offset:34848
	ds_read_b128 v[152:155], v243 offset:39424
	ds_read_b128 v[156:159], v243 offset:39456
	v_cvt_pk_bf16_f32 v162, v68, v69
	v_cvt_pk_bf16_f32 v163, v70, v71
	v_cvt_pk_bf16_f32 v164, v72, v73
	v_cvt_pk_bf16_f32 v165, v74, v75
	v_cvt_pk_bf16_f32 v166, v76, v77
	v_cvt_pk_bf16_f32 v167, v78, v79
	s_nop 4
	v_exp_f32_e32 v80, v80
	v_exp_f32_e32 v81, v81
	v_exp_f32_e32 v82, v82
	v_exp_f32_e32 v83, v83
	s_waitcnt lgkmcnt(7)
	v_mfma_f32_32x32x16_bf16 v[16:31], v[128:131], v[160:163], v[16:31]
	s_cmp_eq_u64 s[0:1], 0
	s_cbranch_scc1 .La2t0n_lv_a
	s_waitcnt vmcnt(4)
	s_branch .La2t0n_lv_b

.La2t1_cb:
	ds_read_b128 v[128:131], v243 offset:62464
	ds_read_b128 v[132:135], v243 offset:62496
	ds_read_b128 v[136:139], v244 offset:13824
	ds_read_b128 v[140:143], v244 offset:13856
	s_cmp_eq_u64 s[0:1], 0
	s_waitcnt lgkmcnt(11)
	v_mfma_f32_32x32x16_bf16 v[64:79], v[172:175], v[222:225], v[194:209]
	s_cbranch_scc1 .La2t1_nl0
	global_load_dwordx4 v[104:107], v192, s[84:85]
.La2t1_nl0:
	s_waitcnt lgkmcnt(10)
	v_mfma_f32_32x32x16_bf16 v[64:79], v[168:171], v[218:221], v[64:79]
	s_cbranch_scc1 .La2t1_nl1
	global_load_dwordx4 v[108:111], v193, s[84:85]
.La2t1_nl1:
	s_waitcnt lgkmcnt(9)
	v_mfma_f32_32x32x16_bf16 v[64:79], v[164:167], v[214:217], v[64:79]
	s_cbranch_scc1 .La2t1_nl2
	global_load_dwordx4 v[112:115], v190, s[26:27]
.La2t1_nl2:
	s_waitcnt lgkmcnt(8)
	v_mfma_f32_32x32x16_bf16 v[64:79], v[160:163], v[210:213], v[64:79]
	s_cbranch_scc1 .La2t1_nl3
	global_load_dwordx4 v[116:119], v191, s[26:27]
.La2t1_nl3:
	s_add_u32 s84, s84, 0x10000
	s_addc_u32 s85, s85, 0
	s_add_u32 s26, s26, 0x80
	s_addc_u32 s27, s27, 0
	s_waitcnt lgkmcnt(7)
	v_mfma_f32_32x32x16_bf16 v[80:95], v[156:159], v[222:225], v[194:209]
	s_nop 11
	v_exp_f32_e32 v64, v64
	v_exp_f32_e32 v65, v65
	v_exp_f32_e32 v66, v66
	v_exp_f32_e32 v67, v67
	v_exp_f32_e32 v68, v68
	v_exp_f32_e32 v69, v69
	s_waitcnt lgkmcnt(6)
	v_mfma_f32_32x32x16_bf16 v[80:95], v[152:155], v[218:221], v[80:95]
	v_exp_f32_e32 v70, v70
	v_exp_f32_e32 v71, v71
	v_exp_f32_e32 v72, v72
	v_exp_f32_e32 v73, v73
	v_exp_f32_e32 v74, v74
	v_exp_f32_e32 v75, v75
	s_waitcnt lgkmcnt(5)
	v_mfma_f32_32x32x16_bf16 v[80:95], v[148:151], v[214:217], v[80:95]
	v_exp_f32_e32 v76, v76
	v_exp_f32_e32 v77, v77
	v_exp_f32_e32 v78, v78
	v_exp_f32_e32 v79, v79
	v_cvt_pk_bf16_f32 v160, v64, v65
	v_cvt_pk_bf16_f32 v161, v66, v67
	s_waitcnt lgkmcnt(4)
	v_mfma_f32_32x32x16_bf16 v[80:95], v[144:147], v[210:213], v[80:95]
	ds_read_b128 v[144:147], v243 offset:53248
	ds_read_b128 v[148:151], v243 offset:53280
	ds_read_b128 v[152:155], v243 offset:57856
	ds_read_b128 v[156:159], v243 offset:57888
	v_cvt_pk_bf16_f32 v162, v68, v69
	v_cvt_pk_bf16_f32 v163, v70, v71
	v_cvt_pk_bf16_f32 v164, v72, v73
	v_cvt_pk_bf16_f32 v165, v74, v75
	v_cvt_pk_bf16_f32 v166, v76, v77
	v_cvt_pk_bf16_f32 v167, v78, v79
	s_nop 4
	v_exp_f32_e32 v80, v80
	v_exp_f32_e32 v81, v81
	v_exp_f32_e32 v82, v82
	v_exp_f32_e32 v83, v83
	s_waitcnt lgkmcnt(7)
	v_mfma_f32_32x32x16_bf16 v[16:31], v[128:131], v[160:163], v[16:31]
	s_cmp_eq_u64 s[0:1], 0
	s_cbranch_scc1 .La2t1_lv_s
	s_waitcnt vmcnt(4)
	ds_write_b128 v239, v[96:99]
	ds_write_b128 v239, v[100:103] offset:8704
	ds_write2_b64 v241, v[120:121], v[122:123] offset1:2
	ds_write2_b64 v242, v[124:125], v[126:127] offset0:128 offset1:130

.La2t1_near:
	s_mul_i32 s101, s60, 0x704
	s_add_i32 s101, s101, 0x1b080
	v_lshl_add_u32 v251, v249, 2, s101
	ds_read_b32 v64, v251 offset:0
	ds_read_b32 v65, v251 offset:4
	ds_read_b32 v66, v251 offset:8
	ds_read_b32 v67, v251 offset:12
	ds_read_b32 v68, v251 offset:32
	ds_read_b32 v69, v251 offset:36
	ds_read_b32 v70, v251 offset:40
	ds_read_b32 v71, v251 offset:44
	ds_read_b32 v72, v251 offset:64
	ds_read_b32 v73, v251 offset:68
	ds_read_b32 v74, v251 offset:72
	ds_read_b32 v75, v251 offset:76
	ds_read_b32 v76, v251 offset:96
	ds_read_b32 v77, v251 offset:100
	ds_read_b32 v78, v251 offset:104
	ds_read_b32 v79, v251 offset:108
	ds_read_b32 v80, v251 offset:128
	ds_read_b32 v81, v251 offset:132
	ds_read_b32 v82, v251 offset:136
	ds_read_b32 v83, v251 offset:140
	ds_read_b32 v84, v251 offset:160
	ds_read_b32 v85, v251 offset:164
	ds_read_b32 v86, v251 offset:168
	ds_read_b32 v87, v251 offset:172
	ds_read_b32 v88, v251 offset:192
	ds_read_b32 v89, v251 offset:196
	ds_read_b32 v90, v251 offset:200
	ds_read_b32 v91, v251 offset:204
	ds_read_b32 v92, v251 offset:224
	ds_read_b32 v93, v251 offset:228
	ds_read_b32 v94, v251 offset:232
	ds_read_b32 v95, v251 offset:236
	s_waitcnt lgkmcnt(0)
	ds_read_b128 v[128:131], v243 offset:62464
	ds_read_b128 v[132:135], v243 offset:62496
	ds_read_b128 v[136:139], v244 offset:13824
	ds_read_b128 v[140:143], v244 offset:13856
	s_cmp_eq_u64 s[0:1], 0
	v_mfma_f32_32x32x16_bf16 v[64:79], v[172:175], v[222:225], v[64:79]
	s_cbranch_scc1 .La2t1n_nl0
	global_load_dwordx4 v[104:107], v192, s[84:85]
.La2t1n_nl0:
	v_mfma_f32_32x32x16_bf16 v[64:79], v[168:171], v[218:221], v[64:79]
	s_cbranch_scc1 .La2t1n_nl1
	global_load_dwordx4 v[108:111], v193, s[84:85]
.La2t1n_nl1:
	v_mfma_f32_32x32x16_bf16 v[64:79], v[164:167], v[214:217], v[64:79]
	s_cbranch_scc1 .La2t1n_nl2
	global_load_dwordx4 v[112:115], v190, s[26:27]
.La2t1n_nl2:
	v_mfma_f32_32x32x16_bf16 v[64:79], v[160:163], v[210:213], v[64:79]
	s_cbranch_scc1 .La2t1n_nl3
	global_load_dwordx4 v[116:119], v191, s[26:27]
.La2t1n_nl3:
	s_add_u32 s84, s84, 0x10000
	s_addc_u32 s85, s85, 0
	s_add_u32 s26, s26, 0x80
	s_addc_u32 s27, s27, 0
	v_mfma_f32_32x32x16_bf16 v[80:95], v[156:159], v[222:225], v[80:95]
	s_nop 11
	v_exp_f32_e32 v64, v64
	v_exp_f32_e32 v65, v65
	v_exp_f32_e32 v66, v66
	v_exp_f32_e32 v67, v67
	v_exp_f32_e32 v68, v68
	v_exp_f32_e32 v69, v69
	v_mfma_f32_32x32x16_bf16 v[80:95], v[152:155], v[218:221], v[80:95]
	v_exp_f32_e32 v70, v70
	v_exp_f32_e32 v71, v71
	v_exp_f32_e32 v72, v72
	v_exp_f32_e32 v73, v73
	v_exp_f32_e32 v74, v74
	v_exp_f32_e32 v75, v75
	v_mfma_f32_32x32x16_bf16 v[80:95], v[148:151], v[214:217], v[80:95]
	v_exp_f32_e32 v76, v76
	v_exp_f32_e32 v77, v77
	v_exp_f32_e32 v78, v78
	v_exp_f32_e32 v79, v79
	v_cvt_pk_bf16_f32 v160, v64, v65
	v_cvt_pk_bf16_f32 v161, v66, v67
	v_mfma_f32_32x32x16_bf16 v[80:95], v[144:147], v[210:213], v[80:95]
	ds_read_b128 v[144:147], v243 offset:53248
	ds_read_b128 v[148:151], v243 offset:53280
	ds_read_b128 v[152:155], v243 offset:57856
	ds_read_b128 v[156:159], v243 offset:57888
	v_cvt_pk_bf16_f32 v162, v68, v69
	v_cvt_pk_bf16_f32 v163, v70, v71
	v_cvt_pk_bf16_f32 v164, v72, v73
	v_cvt_pk_bf16_f32 v165, v74, v75
	v_cvt_pk_bf16_f32 v166, v76, v77
	v_cvt_pk_bf16_f32 v167, v78, v79
	s_nop 4
	v_exp_f32_e32 v80, v80
	v_exp_f32_e32 v81, v81
	v_exp_f32_e32 v82, v82
	v_exp_f32_e32 v83, v83
	s_waitcnt lgkmcnt(7)
	v_mfma_f32_32x32x16_bf16 v[16:31], v[128:131], v[160:163], v[16:31]
	s_cmp_eq_u64 s[0:1], 0
	s_cbranch_scc1 .La2t1n_lv_s
	s_waitcnt vmcnt(4)
	ds_write_b128 v239, v[96:99]
	ds_write_b128 v239, v[100:103] offset:8704
	ds_write2_b64 v241, v[120:121], v[122:123] offset1:2
	ds_write2_b64 v242, v[124:125], v[126:127] offset0:128 offset1:130
